# t3 + NA unit->CU remap so each XCD handles one head's contiguous row-blocks (K/V halo shared in L2)
# baseline (speedup 1.0000x reference)
; __device__ __forceinline__ unsigned cvt_pk_bf16(float lo, float hi) { f32x2_t v = {lo, hi}; bf16x2_t r = __builtin_convertvector(v, bf16x2_t); return __builtin_bit_cast(unsigned, r); }
; __device__ __forceinline__ int crow(int r, int hi) { return (r & 3) + 8 * (r >> 2) + 4 * hi; }
; template <int MODE, int SDEPTH, bool SIMPLE>
; __device__ __forceinline__ void attn_body(const Unit& U, char* lds, const int tid) {
;     ...
;   if (hi == 0) li_l[r32] = l_reg; asm volatile("s_waitcnt lgkmcnt(0)" ::: "memory");
;   if constexpr (MODE == 2) { if (hi == 0) U.LSE[(long)(wid * QBLK + r32) * U.ldl] = m_reg * SCALE + __logf(l_reg); }
;   __syncthreads();
;   constexpr int OP = 136;
;   bf16_t* ol = (bf16_t*)lds + wid * (32 * OP);
; #pragma unroll
;   for (int r = 0; r < 16; ++r) { const float rl = __builtin_amdgcn_rcpf(li_l[crow(r, hi)]); bf16_t* op = ol + crow(r, hi) * OP + r32;
; #pragma unroll
;     for (int d0 = 0; d0 < 4; ++d0) op[d0 * 32] = (bf16_t)(cvt_pk_bf16(o[d0][r] * rl, 0.f) & 0xffffu); }
; __global__ void __launch_bounds__(512) mega(Args a) {
;     ...
;       if (P2MASK & 2) for (int un = cu; un < NB * 8 * 32; un += G) {
;         const int qb = un & 31, h = (un >> 5) & 7, b = un >> 8;
;         const int r0 = qb * 4, kr0 = min(max(r0 - 4, 0), 120), krl = min(max(r0 + 3 - 4, 0), 120) + 7;
;         __syncthreads();
;         if (tid < 465) ((float*)(shm + att::SHM_TBL))[tid] = rpb[(size_t)(l * 8 + h) * 465 + tid] * att::ISCALE;
;         att::Unit U{};
.LBB0_279:
	s_or_b64 exec, exec, s[2:3]
	s_cmpk_gt_i32 s22, 0x1ff
	s_cbranch_scc1 .LBB0_298
	v_readlane_b32 s0, v251, 61
	s_add_u32 s0, s0, 0x3d000000
	v_ashrrev_i32_e32 v147, 31, v146
	v_writelane_b32 v250, s0, 0
	v_readlane_b32 s0, v251, 62
	s_addc_u32 s19, s0, 0
	v_readlane_b32 s0, v251, 56
	s_lshl_b32 s0, s0, 3
	v_readlane_b32 s1, v251, 57
	v_writelane_b32 v250, s0, 1
	s_movk_i32 s0, 0x1d1
	v_cmp_gt_i32_e64 s[0:1], s0, v146
	v_lshl_add_u64 v[148:149], v[146:147], 2, s[92:93]
	s_lshl_b32 s21, s22, 2
	v_writelane_b32 v250, s0, 2
	s_mov_b32 s17, s22
	v_writelane_b32 v250, s22, 31
	s_nop 0
	v_writelane_b32 v250, s1, 3
	v_readlane_b32 s0, v251, 10
	s_nop 1
	v_lshl_add_u32 v147, v146, 2, s0
	v_readlane_b32 s0, v251, 63
	s_lshl_b32 s16, s0, 2
	v_readlane_b32 s0, v251, 6
	s_add_u32 s0, s0, s30
	s_nop 0
	v_writelane_b32 v250, s0, 4
	v_readlane_b32 s0, v251, 7
	s_addc_u32 s0, s0, 0
	s_nop 0
	v_writelane_b32 v250, s0, 5
	s_branch .LBB0_282
.LBB0_281:
	s_or_b64 exec, exec, s[0:1]
	v_lshl_add_u32 v65, v156, 4, v157
	s_waitcnt lgkmcnt(0)
	s_waitcnt lgkmcnt(0)
	s_barrier
	ds_read_b128 v[66:69], v65
	s_mul_i32 s0, s3, 0x1400
	s_mul_hi_u32 s1, s20, 0x1400
	s_add_i32 s1, s1, s0
	s_mulk_i32 s20, 0x1400
	s_waitcnt lgkmcnt(0)
	v_rcp_f32_e32 v66, v66
	v_readlane_b32 s0, v250, 0
	s_movk_i32 s4, 0x2200
	s_add_u32 s0, s0, s20
	v_mul_lo_u32 v64, v158, s4
	s_addc_u32 s1, s19, s1
	s_lshl_b32 s2, s27, 1
	v_add_u32_e32 v64, 0, v64
	s_add_u32 s0, s0, s2
	v_lshl_add_u32 v70, v159, 1, v64
	s_movk_i32 s4, 0x440
	v_mul_f32_e32 v0, v0, v66
	v_mad_u32_u24 v71, v156, s4, v70
	v_cvt_pk_bf16_f32 v0, v0, s0
	ds_write_b16 v71, v0
	v_mul_f32_e32 v0, v48, v66
	v_cvt_pk_bf16_f32 v0, v0, s0
	ds_write_b16 v71, v0 offset:64
	v_mul_f32_e32 v0, v32, v66
	v_cvt_pk_bf16_f32 v0, v0, s0
	v_rcp_f32_e32 v32, v67
	ds_write_b16 v71, v0 offset:128
	v_mul_f32_e32 v0, v16, v66
	v_cvt_pk_bf16_f32 v0, v0, s0
	ds_write_b16 v71, v0 offset:192
	v_lshl_or_b32 v0, v156, 2, 1
	s_movk_i32 s4, 0x110
	v_mad_u32_u24 v16, v0, s4, v70
	v_mul_f32_e32 v0, v1, v32
	v_cvt_pk_bf16_f32 v0, v0, s0
	ds_write_b16 v16, v0
	v_mul_f32_e32 v0, v49, v32
	v_cvt_pk_bf16_f32 v0, v0, s0
	ds_write_b16 v16, v0 offset:64
	v_mul_f32_e32 v0, v33, v32
	v_cvt_pk_bf16_f32 v0, v0, s0
	ds_write_b16 v16, v0 offset:128
	v_mul_f32_e32 v0, v17, v32
	v_cvt_pk_bf16_f32 v0, v0, s0
	ds_write_b16 v16, v0 offset:192
	v_rcp_f32_e32 v0, v68
	s_addc_u32 s1, s1, 0
	s_add_u32 s2, s26, s2
	s_addc_u32 s3, s24, 0
	v_mul_f32_e32 v1, v2, v0
	v_cvt_pk_bf16_f32 v1, v1, s0
	ds_write_b16 v16, v1 offset:272
	v_mul_f32_e32 v1, v50, v0
	v_cvt_pk_bf16_f32 v1, v1, s0
	ds_write_b16 v16, v1 offset:336
	v_mul_f32_e32 v1, v34, v0
	v_mul_f32_e32 v0, v18, v0
	v_cvt_pk_bf16_f32 v0, v0, s0
	ds_write_b16 v16, v0 offset:464
	v_rcp_f32_e32 v0, v69
	v_cvt_pk_bf16_f32 v1, v1, s0
	ds_write_b16 v16, v1 offset:400
	s_add_i32 s21, s21, s16
	v_mul_f32_e32 v1, v3, v0
	v_cvt_pk_bf16_f32 v1, v1, s0
	ds_write_b16 v16, v1 offset:544
	v_mul_f32_e32 v1, v51, v0
	v_cvt_pk_bf16_f32 v1, v1, s0
	ds_write_b16 v16, v1 offset:608
	v_mul_f32_e32 v1, v35, v0
	v_mul_f32_e32 v0, v19, v0
	v_cvt_pk_bf16_f32 v1, v1, s0
	v_cvt_pk_bf16_f32 v0, v0, s0
	ds_write_b16 v16, v1 offset:672
	ds_write_b16 v16, v0 offset:736
	ds_read_b128 v[0:3], v65 offset:32
	s_movk_i32 s69, 0x1400
	s_waitcnt lgkmcnt(0)
	v_rcp_f32_e32 v0, v0
	s_nop 0
	v_mul_f32_e32 v4, v4, v0
	v_cvt_pk_bf16_f32 v4, v4, s0
	ds_write_b16 v16, v4 offset:1904
	v_mul_f32_e32 v4, v52, v0
	v_cvt_pk_bf16_f32 v4, v4, s0
	ds_write_b16 v16, v4 offset:1968
	v_mul_f32_e32 v4, v36, v0
	v_mul_f32_e32 v0, v20, v0
	v_cvt_pk_bf16_f32 v0, v0, s0
	ds_write_b16 v16, v0 offset:2096
	v_rcp_f32_e32 v0, v1
	v_cvt_pk_bf16_f32 v4, v4, s0
	ds_write_b16 v16, v4 offset:2032
	v_mul_f32_e32 v1, v5, v0
	v_cvt_pk_bf16_f32 v1, v1, s0
	ds_write_b16 v16, v1 offset:2176
	v_mul_f32_e32 v1, v53, v0
	v_cvt_pk_bf16_f32 v1, v1, s0
	ds_write_b16 v16, v1 offset:2240
	v_mul_f32_e32 v1, v37, v0
	v_mul_f32_e32 v0, v21, v0
	v_cvt_pk_bf16_f32 v0, v0, s0
	ds_write_b16 v16, v0 offset:2368
	v_rcp_f32_e32 v0, v2
	v_cvt_pk_bf16_f32 v1, v1, s0
	ds_write_b16 v16, v1 offset:2304
	v_mul_f32_e32 v1, v6, v0
	v_cvt_pk_bf16_f32 v1, v1, s0
	ds_write_b16 v16, v1 offset:2448
	v_mul_f32_e32 v1, v54, v0
	v_cvt_pk_bf16_f32 v1, v1, s0
	ds_write_b16 v16, v1 offset:2512
	v_mul_f32_e32 v1, v38, v0
	v_mul_f32_e32 v0, v22, v0
	v_cvt_pk_bf16_f32 v0, v0, s0
	ds_write_b16 v16, v0 offset:2640
	v_rcp_f32_e32 v0, v3
	v_cvt_pk_bf16_f32 v1, v1, s0
	ds_write_b16 v16, v1 offset:2576
	v_mul_f32_e32 v1, v7, v0
	v_cvt_pk_bf16_f32 v1, v1, s0
	ds_write_b16 v16, v1 offset:2720
	v_mul_f32_e32 v1, v55, v0
	v_cvt_pk_bf16_f32 v1, v1, s0
	ds_write_b16 v16, v1 offset:2784
	v_mul_f32_e32 v1, v39, v0
	v_mul_f32_e32 v0, v23, v0
	v_cvt_pk_bf16_f32 v1, v1, s0
	v_cvt_pk_bf16_f32 v0, v0, s0
	ds_write_b16 v16, v1 offset:2848
	ds_write_b16 v16, v0 offset:2912
	ds_read_b128 v[0:3], v65 offset:64
	s_waitcnt lgkmcnt(0)
; __device__ __forceinline__ unsigned cvt_pk_bf16(float lo, float hi) { f32x2_t v = {lo, hi}; bf16x2_t r = __builtin_convertvector(v, bf16x2_t); return __builtin_bit_cast(unsigned, r); }
; __device__ __forceinline__ float bf_lo(unsigned w) { return __uint_as_float(w << 16); }
; __device__ __forceinline__ float bf_hi(unsigned w) { return __uint_as_float(w & 0xffff0000u); }
; __device__ __forceinline__ int crow(int r, int hi) { return (r & 3) + 8 * (r >> 2) + 4 * hi; }
; template <int MODE, int SDEPTH, bool SIMPLE>
; __device__ __forceinline__ void attn_body(const Unit& U, char* lds, const int tid) {
;     ...
;   for (int r = 0; r < 16; ++r) { const float rl = __builtin_amdgcn_rcpf(li_l[crow(r, hi)]); bf16_t* op = ol + crow(r, hi) * OP + r32;
; #pragma unroll
;     for (int d0 = 0; d0 < 4; ++d0) op[d0 * 32] = (bf16_t)(cvt_pk_bf16(o[d0][r] * rl, 0.f) & 0xffffu); }
;   asm volatile("s_waitcnt lgkmcnt(0)" ::: "memory");
;   { const int cc = (lane & 15) * 8, rb = lane >> 4;
;     u32x4 zz[8];
;     if constexpr (MODE != 2) {
; #pragma unroll
;       for (int i = 0; i < 8; ++i) zz[i] = *(const u32x4*)(U.Z + (long)(wid * QBLK + rb + 4 * i) * U.ldz + cc);
;     }
; #pragma unroll
;     for (int i = 0; i < 8; ++i) { const int row = rb + 4 * i; const long orow = wid * QBLK + row;
;       u32x4 v = *(const u32x4*)(ol + row * OP + cc);
;       if constexpr (MODE != 2) { const u32x4 z = zz[i];
; #pragma unroll
;         for (int q = 0; q < 4; ++q) v[q] = cvt_pk_bf16(bf_lo(v[q]) * bf_lo(z[q]), bf_hi(v[q]) * bf_hi(z[q])); }
;       *(u32x4*)(U.O + orow * U.ldo + cc) = v; } }
	v_rcp_f32_e32 v0, v0
	s_nop 0
	v_mul_f32_e32 v4, v8, v0
	v_cvt_pk_bf16_f32 v4, v4, s0
	ds_write_b16 v16, v4 offset:4080
	v_mul_f32_e32 v4, v56, v0
	v_cvt_pk_bf16_f32 v4, v4, s0
	ds_write_b16 v16, v4 offset:4144
	v_mul_f32_e32 v4, v40, v0
	v_mul_f32_e32 v0, v24, v0
	v_cvt_pk_bf16_f32 v0, v0, s0
	ds_write_b16 v16, v0 offset:4272
	v_rcp_f32_e32 v0, v1
	v_cvt_pk_bf16_f32 v4, v4, s0
	ds_write_b16 v16, v4 offset:4208
	v_mul_f32_e32 v1, v9, v0
	v_cvt_pk_bf16_f32 v1, v1, s0
	ds_write_b16 v16, v1 offset:4352
	v_mul_f32_e32 v1, v57, v0
	v_cvt_pk_bf16_f32 v1, v1, s0
	ds_write_b16 v16, v1 offset:4416
	v_mul_f32_e32 v1, v41, v0
	v_mul_f32_e32 v0, v25, v0
	v_cvt_pk_bf16_f32 v0, v0, s0
	ds_write_b16 v16, v0 offset:4544
	v_rcp_f32_e32 v0, v2
	v_cvt_pk_bf16_f32 v1, v1, s0
	ds_write_b16 v16, v1 offset:4480
	v_mul_f32_e32 v1, v10, v0
	v_cvt_pk_bf16_f32 v1, v1, s0
	ds_write_b16 v16, v1 offset:4624
	v_mul_f32_e32 v1, v58, v0
	v_cvt_pk_bf16_f32 v1, v1, s0
	ds_write_b16 v16, v1 offset:4688
	v_mul_f32_e32 v1, v42, v0
	v_mul_f32_e32 v0, v26, v0
	v_cvt_pk_bf16_f32 v0, v0, s0
	ds_write_b16 v16, v0 offset:4816
	v_rcp_f32_e32 v0, v3
	v_cvt_pk_bf16_f32 v1, v1, s0
	ds_write_b16 v16, v1 offset:4752
	v_mul_f32_e32 v1, v11, v0
	v_cvt_pk_bf16_f32 v1, v1, s0
	ds_write_b16 v16, v1 offset:4896
	v_mul_f32_e32 v1, v59, v0
	v_cvt_pk_bf16_f32 v1, v1, s0
	ds_write_b16 v16, v1 offset:4960
	v_mul_f32_e32 v1, v43, v0
	v_mul_f32_e32 v0, v27, v0
	v_cvt_pk_bf16_f32 v1, v1, s0
	v_cvt_pk_bf16_f32 v0, v0, s0
	ds_write_b16 v16, v1 offset:5024
	ds_write_b16 v16, v0 offset:5088
	ds_read_b128 v[0:3], v65 offset:96
	s_waitcnt lgkmcnt(0)
	v_rcp_f32_e32 v0, v0
	s_nop 0
	v_mul_f32_e32 v4, v12, v0
	v_cvt_pk_bf16_f32 v4, v4, s0
	ds_write_b16 v16, v4 offset:6256
	v_mul_f32_e32 v4, v60, v0
	v_cvt_pk_bf16_f32 v4, v4, s0
	ds_write_b16 v16, v4 offset:6320
	v_mul_f32_e32 v4, v44, v0
	v_mul_f32_e32 v0, v28, v0
	v_cvt_pk_bf16_f32 v0, v0, s0
	ds_write_b16 v16, v0 offset:6448
	v_rcp_f32_e32 v0, v1
	v_cvt_pk_bf16_f32 v4, v4, s0
	v_lshrrev_b32_e32 v28, 4, v154
	ds_write_b16 v16, v4 offset:6384
	v_mul_f32_e32 v1, v13, v0
	v_cvt_pk_bf16_f32 v1, v1, s0
	ds_write_b16 v16, v1 offset:6528
	v_mul_f32_e32 v1, v61, v0
	v_cvt_pk_bf16_f32 v1, v1, s0
	ds_write_b16 v16, v1 offset:6592
	v_mul_f32_e32 v1, v45, v0
	v_mul_f32_e32 v0, v29, v0
	v_cvt_pk_bf16_f32 v0, v0, s0
	ds_write_b16 v16, v0 offset:6720
	v_rcp_f32_e32 v0, v2
	v_cvt_pk_bf16_f32 v1, v1, s0
	ds_write_b16 v16, v1 offset:6656
	v_mul_f32_e32 v1, v14, v0
	v_cvt_pk_bf16_f32 v1, v1, s0
	ds_write_b16 v16, v1 offset:6800
	v_mul_f32_e32 v1, v62, v0
	v_cvt_pk_bf16_f32 v1, v1, s0
	ds_write_b16 v16, v1 offset:6864
	v_mul_f32_e32 v1, v46, v0
	v_mul_f32_e32 v0, v30, v0
	v_cvt_pk_bf16_f32 v0, v0, s0
	ds_write_b16 v16, v0 offset:6992
	v_rcp_f32_e32 v0, v3
	v_cvt_pk_bf16_f32 v1, v1, s0
	ds_write_b16 v16, v1 offset:6928
	v_or_b32_e32 v46, v28, v155
	v_mul_f32_e32 v1, v15, v0
	v_cvt_pk_bf16_f32 v1, v1, s0
	ds_write_b16 v16, v1 offset:7072
	v_mul_f32_e32 v1, v63, v0
	v_cvt_pk_bf16_f32 v1, v1, s0
	ds_write_b16 v16, v1 offset:7136
	v_mul_f32_e32 v1, v47, v0
	v_mul_f32_e32 v0, v31, v0
	v_cvt_pk_bf16_f32 v1, v1, s0
	v_cvt_pk_bf16_f32 v0, v0, s0
	ds_write_b16 v16, v1 offset:7200
	ds_write_b16 v16, v0 offset:7264
	v_lshl_add_u64 v[0:1], s[2:3], 0, v[192:193]
	s_mov_b64 s[2:3], 0x4800
	v_lshl_add_u64 v[0:1], v[0:1], 0, s[2:3]
	s_waitcnt lgkmcnt(0)
	v_mad_i64_i32 v[2:3], s[2:3], v46, s14, v[0:1]
	global_load_dwordx4 v[36:39], v[2:3], off
	v_or_b32_e32 v47, 4, v46
	v_mad_i64_i32 v[2:3], s[2:3], v47, s14, v[0:1]
	global_load_dwordx4 v[24:27], v[2:3], off
	v_or_b32_e32 v48, 8, v46
	v_mad_i64_i32 v[2:3], s[2:3], v48, s14, v[0:1]
	global_load_dwordx4 v[20:23], v[2:3], off
	v_or_b32_e32 v35, 12, v46
	v_mad_i64_i32 v[2:3], s[2:3], v35, s14, v[0:1]
	global_load_dwordx4 v[16:19], v[2:3], off
	v_or_b32_e32 v34, 16, v46
	v_mad_i64_i32 v[2:3], s[2:3], v34, s14, v[0:1]
	global_load_dwordx4 v[12:15], v[2:3], off
	v_mul_u32_u24_e32 v28, 0x110, v28
	v_or_b32_e32 v33, 20, v46
	v_add3_u32 v31, v64, v192, v28
	v_mad_i64_i32 v[2:3], s[2:3], v33, s14, v[0:1]
	ds_read_b128 v[40:43], v31
	global_load_dwordx4 v[8:11], v[2:3], off
	v_or_b32_e32 v32, 24, v46
	v_or_b32_e32 v30, 28, v46
	v_mad_i64_i32 v[2:3], s[2:3], v32, s14, v[0:1]
	s_waitcnt lgkmcnt(0)
	v_lshlrev_b32_e32 v28, 16, v40
	v_and_b32_e32 v29, 0xffff0000, v40
	v_mad_i64_i32 v[0:1], s[2:3], v30, s14, v[0:1]
	s_movk_i32 s2, 0x1400
	global_load_dwordx4 v[4:7], v[2:3], off
	s_waitcnt vmcnt(6)
	v_lshlrev_b32_e32 v44, 16, v36
	v_and_b32_e32 v45, 0xffff0000, v36
	v_pk_mul_f32 v[28:29], v[44:45], v[28:29]
	v_lshlrev_b32_e32 v40, 16, v37
	v_cvt_pk_bf16_f32 v36, v28, v29
	v_lshlrev_b32_e32 v28, 16, v41
	v_and_b32_e32 v29, 0xffff0000, v41
	v_and_b32_e32 v41, 0xffff0000, v37
	v_pk_mul_f32 v[28:29], v[40:41], v[28:29]
	v_lshlrev_b32_e32 v40, 16, v38
	v_cvt_pk_bf16_f32 v37, v28, v29
	v_lshlrev_b32_e32 v28, 16, v42
	v_and_b32_e32 v29, 0xffff0000, v42
	v_and_b32_e32 v41, 0xffff0000, v38
	v_pk_mul_f32 v[28:29], v[40:41], v[28:29]
	v_lshlrev_b32_e32 v40, 16, v39
	v_cvt_pk_bf16_f32 v38, v28, v29
	v_lshlrev_b32_e32 v28, 16, v43
	v_and_b32_e32 v29, 0xffff0000, v43
	v_and_b32_e32 v41, 0xffff0000, v39
	v_pk_mul_f32 v[28:29], v[40:41], v[28:29]
	global_load_dwordx4 v[0:3], v[0:1], off
	v_cvt_pk_bf16_f32 v39, v28, v29
	v_mov_b64_e32 v[28:29], s[0:1]
	v_mad_i64_i32 v[40:41], s[0:1], v46, s2, v[28:29]
	v_lshl_add_u64 v[40:41], v[40:41], 0, v[192:193]
	global_store_dwordx4 v[40:41], v[36:39], off sc1
	ds_read_b128 v[36:39], v31 offset:1088
	s_waitcnt vmcnt(7)
	v_lshlrev_b32_e32 v42, 16, v24
	v_and_b32_e32 v43, 0xffff0000, v24
	s_waitcnt lgkmcnt(0)
; __device__ __forceinline__ unsigned cvt_pk_bf16(float lo, float hi) { f32x2_t v = {lo, hi}; bf16x2_t r = __builtin_convertvector(v, bf16x2_t); return __builtin_bit_cast(unsigned, r); }
; __device__ __forceinline__ float bf_lo(unsigned w) { return __uint_as_float(w << 16); }
; __device__ __forceinline__ float bf_hi(unsigned w) { return __uint_as_float(w & 0xffff0000u); }
; template <int MODE, int SDEPTH, bool SIMPLE>
; __device__ __forceinline__ void attn_body(const Unit& U, char* lds, const int tid) {
;     ...
;     for (int i = 0; i < 8; ++i) { const int row = rb + 4 * i; const long orow = wid * QBLK + row;
;       u32x4 v = *(const u32x4*)(ol + row * OP + cc);
;       if constexpr (MODE != 2) { const u32x4 z = zz[i];
; #pragma unroll
;         for (int q = 0; q < 4; ++q) v[q] = cvt_pk_bf16(bf_lo(v[q]) * bf_lo(z[q]), bf_hi(v[q]) * bf_hi(z[q])); }
;       *(u32x4*)(U.O + orow * U.ldo + cc) = v; } }
	v_lshlrev_b32_e32 v40, 16, v36
	v_and_b32_e32 v41, 0xffff0000, v36
	v_pk_mul_f32 v[40:41], v[42:43], v[40:41]
	v_lshlrev_b32_e32 v36, 16, v37
	v_cvt_pk_bf16_f32 v24, v40, v41
	v_and_b32_e32 v37, 0xffff0000, v37
	v_lshlrev_b32_e32 v40, 16, v25
	v_and_b32_e32 v41, 0xffff0000, v25
	v_pk_mul_f32 v[36:37], v[40:41], v[36:37]
	v_lshlrev_b32_e32 v40, 16, v26
	v_cvt_pk_bf16_f32 v25, v36, v37
	v_lshlrev_b32_e32 v36, 16, v38
	v_and_b32_e32 v37, 0xffff0000, v38
	v_and_b32_e32 v41, 0xffff0000, v26
	v_pk_mul_f32 v[36:37], v[40:41], v[36:37]
	v_lshlrev_b32_e32 v38, 16, v27
	v_cvt_pk_bf16_f32 v26, v36, v37
	v_lshlrev_b32_e32 v36, 16, v39
	v_and_b32_e32 v37, 0xffff0000, v39
	v_and_b32_e32 v39, 0xffff0000, v27
	v_pk_mul_f32 v[36:37], v[38:39], v[36:37]
	s_waitcnt vmcnt(6)
	v_lshlrev_b32_e32 v38, 16, v20
	v_cvt_pk_bf16_f32 v27, v36, v37
	v_mad_i64_i32 v[36:37], s[0:1], v47, s2, v[28:29]
	v_lshl_add_u64 v[36:37], v[36:37], 0, v[192:193]
	global_store_dwordx4 v[36:37], v[24:27], off sc1
	ds_read_b128 v[24:27], v31 offset:2176
	v_and_b32_e32 v39, 0xffff0000, v20
	s_waitcnt lgkmcnt(0)
	v_lshlrev_b32_e32 v36, 16, v24
	v_and_b32_e32 v37, 0xffff0000, v24
	v_pk_mul_f32 v[36:37], v[38:39], v[36:37]
	v_lshlrev_b32_e32 v24, 16, v25
	v_cvt_pk_bf16_f32 v20, v36, v37
	v_and_b32_e32 v25, 0xffff0000, v25
	v_lshlrev_b32_e32 v36, 16, v21
	v_and_b32_e32 v37, 0xffff0000, v21
	v_pk_mul_f32 v[24:25], v[36:37], v[24:25]
	v_lshlrev_b32_e32 v36, 16, v22
	v_cvt_pk_bf16_f32 v21, v24, v25
	v_lshlrev_b32_e32 v24, 16, v26
	v_and_b32_e32 v25, 0xffff0000, v26
	v_and_b32_e32 v37, 0xffff0000, v22
	v_pk_mul_f32 v[24:25], v[36:37], v[24:25]
	v_lshlrev_b32_e32 v26, 16, v23
	v_cvt_pk_bf16_f32 v22, v24, v25
	v_lshlrev_b32_e32 v24, 16, v27
	v_and_b32_e32 v25, 0xffff0000, v27
	v_and_b32_e32 v27, 0xffff0000, v23
	v_pk_mul_f32 v[24:25], v[26:27], v[24:25]
	s_waitcnt vmcnt(6)
	v_lshlrev_b32_e32 v26, 16, v16
	v_cvt_pk_bf16_f32 v23, v24, v25
	v_mad_i64_i32 v[24:25], s[0:1], v48, s2, v[28:29]
	v_lshl_add_u64 v[24:25], v[24:25], 0, v[192:193]
	global_store_dwordx4 v[24:25], v[20:23], off sc1
	ds_read_b128 v[20:23], v31 offset:3264
	v_and_b32_e32 v27, 0xffff0000, v16
	s_waitcnt lgkmcnt(0)
	v_lshlrev_b32_e32 v24, 16, v20
	v_and_b32_e32 v25, 0xffff0000, v20
	v_pk_mul_f32 v[24:25], v[26:27], v[24:25]
	v_lshlrev_b32_e32 v20, 16, v21
	v_cvt_pk_bf16_f32 v16, v24, v25
	v_and_b32_e32 v21, 0xffff0000, v21
	v_lshlrev_b32_e32 v24, 16, v17
	v_and_b32_e32 v25, 0xffff0000, v17
	v_pk_mul_f32 v[20:21], v[24:25], v[20:21]
	v_lshlrev_b32_e32 v24, 16, v18
	v_cvt_pk_bf16_f32 v17, v20, v21
	v_lshlrev_b32_e32 v20, 16, v22
	v_and_b32_e32 v21, 0xffff0000, v22
	v_and_b32_e32 v25, 0xffff0000, v18
	v_pk_mul_f32 v[20:21], v[24:25], v[20:21]
	v_lshlrev_b32_e32 v22, 16, v19
	v_cvt_pk_bf16_f32 v18, v20, v21
	v_lshlrev_b32_e32 v20, 16, v23
	v_and_b32_e32 v21, 0xffff0000, v23
	v_and_b32_e32 v23, 0xffff0000, v19
	v_pk_mul_f32 v[20:21], v[22:23], v[20:21]
	s_waitcnt vmcnt(6)
	v_lshlrev_b32_e32 v22, 16, v12
	v_cvt_pk_bf16_f32 v19, v20, v21
	v_mad_i64_i32 v[20:21], s[0:1], v35, s2, v[28:29]
	v_lshl_add_u64 v[20:21], v[20:21], 0, v[192:193]
	global_store_dwordx4 v[20:21], v[16:19], off sc1
	ds_read_b128 v[16:19], v31 offset:4352
	v_and_b32_e32 v23, 0xffff0000, v12
	s_waitcnt lgkmcnt(0)
	v_lshlrev_b32_e32 v20, 16, v16
	v_and_b32_e32 v21, 0xffff0000, v16
	v_pk_mul_f32 v[20:21], v[22:23], v[20:21]
	v_lshlrev_b32_e32 v16, 16, v17
	v_cvt_pk_bf16_f32 v12, v20, v21
	v_and_b32_e32 v17, 0xffff0000, v17
	v_lshlrev_b32_e32 v20, 16, v13
	v_and_b32_e32 v21, 0xffff0000, v13
	v_pk_mul_f32 v[16:17], v[20:21], v[16:17]
	v_lshlrev_b32_e32 v20, 16, v14
	v_cvt_pk_bf16_f32 v13, v16, v17
	v_lshlrev_b32_e32 v16, 16, v18
	v_and_b32_e32 v17, 0xffff0000, v18
	v_and_b32_e32 v21, 0xffff0000, v14
	v_pk_mul_f32 v[16:17], v[20:21], v[16:17]
	v_lshlrev_b32_e32 v18, 16, v15
	v_cvt_pk_bf16_f32 v14, v16, v17
	v_lshlrev_b32_e32 v16, 16, v19
	v_and_b32_e32 v17, 0xffff0000, v19
	v_and_b32_e32 v19, 0xffff0000, v15
	v_pk_mul_f32 v[16:17], v[18:19], v[16:17]
	s_waitcnt vmcnt(6)
; __device__ __forceinline__ unsigned cvt_pk_bf16(float lo, float hi) { f32x2_t v = {lo, hi}; bf16x2_t r = __builtin_convertvector(v, bf16x2_t); return __builtin_bit_cast(unsigned, r); }
; __device__ __forceinline__ float bf_lo(unsigned w) { return __uint_as_float(w << 16); }
; __device__ __forceinline__ float bf_hi(unsigned w) { return __uint_as_float(w & 0xffff0000u); }
; template <int MODE, int SDEPTH, bool SIMPLE>
; __device__ __forceinline__ void attn_body(const Unit& U, char* lds, const int tid) {
;     ...
;     for (int i = 0; i < 8; ++i) { const int row = rb + 4 * i; const long orow = wid * QBLK + row;
;       u32x4 v = *(const u32x4*)(ol + row * OP + cc);
;       if constexpr (MODE != 2) { const u32x4 z = zz[i];
; #pragma unroll
;         for (int q = 0; q < 4; ++q) v[q] = cvt_pk_bf16(bf_lo(v[q]) * bf_lo(z[q]), bf_hi(v[q]) * bf_hi(z[q])); }
;       *(u32x4*)(U.O + orow * U.ldo + cc) = v; } }
; __global__ void __launch_bounds__(512) mega(Args a) {
;     ...
;       if (P2MASK & 2) for (int un = cu; un < NB * 8 * 32; un += G) {
;         const int qb = un & 31, h = (un >> 5) & 7, b = un >> 8;
;         const int r0 = qb * 4, kr0 = min(max(r0 - 4, 0), 120), krl = min(max(r0 + 3 - 4, 0), 120) + 7;
;         __syncthreads();
;         if (tid < 465) ((float*)(shm + att::SHM_TBL))[tid] = rpb[(size_t)(l * 8 + h) * 465 + tid] * att::ISCALE;
;         att::Unit U{};
	v_lshlrev_b32_e32 v18, 16, v8
	v_cvt_pk_bf16_f32 v15, v16, v17
	v_mad_i64_i32 v[16:17], s[0:1], v34, s2, v[28:29]
	v_lshl_add_u64 v[16:17], v[16:17], 0, v[192:193]
	global_store_dwordx4 v[16:17], v[12:15], off sc1
	ds_read_b128 v[12:15], v31 offset:5440
	v_and_b32_e32 v19, 0xffff0000, v8
	s_waitcnt lgkmcnt(0)
	v_lshlrev_b32_e32 v16, 16, v12
	v_and_b32_e32 v17, 0xffff0000, v12
	v_pk_mul_f32 v[16:17], v[18:19], v[16:17]
	v_lshlrev_b32_e32 v12, 16, v13
	v_cvt_pk_bf16_f32 v8, v16, v17
	v_and_b32_e32 v13, 0xffff0000, v13
	v_lshlrev_b32_e32 v16, 16, v9
	v_and_b32_e32 v17, 0xffff0000, v9
	v_pk_mul_f32 v[12:13], v[16:17], v[12:13]
	v_lshlrev_b32_e32 v16, 16, v10
	v_cvt_pk_bf16_f32 v9, v12, v13
	v_lshlrev_b32_e32 v12, 16, v14
	v_and_b32_e32 v13, 0xffff0000, v14
	v_and_b32_e32 v17, 0xffff0000, v10
	v_pk_mul_f32 v[12:13], v[16:17], v[12:13]
	v_lshlrev_b32_e32 v14, 16, v11
	v_cvt_pk_bf16_f32 v10, v12, v13
	v_lshlrev_b32_e32 v12, 16, v15
	v_and_b32_e32 v13, 0xffff0000, v15
	v_and_b32_e32 v15, 0xffff0000, v11
	v_pk_mul_f32 v[12:13], v[14:15], v[12:13]
	s_waitcnt vmcnt(6)
	v_lshlrev_b32_e32 v14, 16, v4
	v_cvt_pk_bf16_f32 v11, v12, v13
	v_mad_i64_i32 v[12:13], s[0:1], v33, s2, v[28:29]
	v_lshl_add_u64 v[12:13], v[12:13], 0, v[192:193]
	global_store_dwordx4 v[12:13], v[8:11], off sc1
	ds_read_b128 v[8:11], v31 offset:6528
	v_and_b32_e32 v15, 0xffff0000, v4
	s_waitcnt lgkmcnt(0)
	v_lshlrev_b32_e32 v12, 16, v8
	v_and_b32_e32 v13, 0xffff0000, v8
	v_pk_mul_f32 v[12:13], v[14:15], v[12:13]
	v_lshlrev_b32_e32 v8, 16, v9
	v_cvt_pk_bf16_f32 v4, v12, v13
	v_and_b32_e32 v9, 0xffff0000, v9
	v_lshlrev_b32_e32 v12, 16, v5
	v_and_b32_e32 v13, 0xffff0000, v5
	v_pk_mul_f32 v[8:9], v[12:13], v[8:9]
	v_lshlrev_b32_e32 v12, 16, v6
	v_cvt_pk_bf16_f32 v5, v8, v9
	v_lshlrev_b32_e32 v8, 16, v10
	v_and_b32_e32 v9, 0xffff0000, v10
	v_and_b32_e32 v13, 0xffff0000, v6
	v_pk_mul_f32 v[8:9], v[12:13], v[8:9]
	v_lshlrev_b32_e32 v10, 16, v7
	v_cvt_pk_bf16_f32 v6, v8, v9
	v_lshlrev_b32_e32 v8, 16, v11
	v_and_b32_e32 v9, 0xffff0000, v11
	v_and_b32_e32 v11, 0xffff0000, v7
	v_pk_mul_f32 v[8:9], v[10:11], v[8:9]
	s_waitcnt vmcnt(6)
	v_lshlrev_b32_e32 v10, 16, v0
	v_cvt_pk_bf16_f32 v7, v8, v9
	v_mad_i64_i32 v[8:9], s[0:1], v32, s2, v[28:29]
	v_lshl_add_u64 v[8:9], v[8:9], 0, v[192:193]
	global_store_dwordx4 v[8:9], v[4:7], off sc1
	ds_read_b128 v[4:7], v31 offset:7616
	v_and_b32_e32 v11, 0xffff0000, v0
	s_waitcnt lgkmcnt(0)
	v_lshlrev_b32_e32 v8, 16, v4
	v_and_b32_e32 v9, 0xffff0000, v4
	v_pk_mul_f32 v[8:9], v[10:11], v[8:9]
	v_lshlrev_b32_e32 v4, 16, v5
	v_cvt_pk_bf16_f32 v0, v8, v9
	v_and_b32_e32 v5, 0xffff0000, v5
	v_lshlrev_b32_e32 v8, 16, v1
	v_and_b32_e32 v9, 0xffff0000, v1
	v_pk_mul_f32 v[4:5], v[8:9], v[4:5]
	v_lshlrev_b32_e32 v8, 16, v2
	v_cvt_pk_bf16_f32 v1, v4, v5
	v_lshlrev_b32_e32 v4, 16, v6
	v_and_b32_e32 v5, 0xffff0000, v6
	v_and_b32_e32 v9, 0xffff0000, v2
	v_pk_mul_f32 v[4:5], v[8:9], v[4:5]
	v_lshlrev_b32_e32 v6, 16, v3
	v_cvt_pk_bf16_f32 v2, v4, v5
	v_lshlrev_b32_e32 v4, 16, v7
	v_and_b32_e32 v5, 0xffff0000, v7
	v_and_b32_e32 v7, 0xffff0000, v3
	v_pk_mul_f32 v[4:5], v[6:7], v[4:5]
	s_nop 0
	v_cvt_pk_bf16_f32 v3, v4, v5
	v_mad_i64_i32 v[4:5], s[0:1], v30, s2, v[28:29]
	v_readlane_b32 s0, v251, 63
	v_readlane_b32 s17, v250, 31
	s_add_i32 s17, s17, s0
	v_writelane_b32 v250, s17, 31
	v_lshl_add_u64 v[4:5], v[4:5], 0, v[192:193]
	s_cmpk_gt_i32 s17, 0x1ff
	global_store_dwordx4 v[4:5], v[0:3], off sc1
	s_cbranch_scc1 .LBB0_298
.LBB0_282:
	v_readlane_b32 s17, v250, 31
	s_and_b32 s0, s17, 7
	s_lshl_b32 s0, s0, 5
	s_bfe_u32 s1, s17, 0x50003
	s_and_b32 s17, s17, 0x100
	s_or_b32 s17, s17, s0
	s_or_b32 s17, s17, s1
	s_lshl_b32 s21, s17, 2
	s_bfe_u32 s5, s21, 0x50002
	s_lshl_b32 s15, s5, 2
	s_lshl_b32 s0, s17, 2
	v_sub_u32_e64 v0, s15, 1 clamp
	s_and_b32 s4, s0, 0x7c
	v_readfirstlane_b32 s25, v0
	v_sub_u32_e64 v0, s4, 1 clamp
	s_bfe_u32 s27, s17, 0x30005
	v_readfirstlane_b32 s2, v0
	s_barrier
	s_mov_b64 s[0:1], exec
	v_readlane_b32 s8, v250, 2
	v_readlane_b32 s9, v250, 3
	s_and_b64 s[8:9], s[0:1], s[8:9]
	s_mov_b64 exec, s[8:9]
	s_cbranch_execz .LBB0_284
	v_readlane_b32 s3, v250, 1
	s_or_b32 s3, s27, s3
	s_nop 0
	v_mad_i64_i32 v[0:1], s[8:9], s3, v229, v[148:149]
	global_load_dword v0, v[0:1], off
	s_waitcnt vmcnt(0)
	v_mul_f32_e32 v0, 0x413504f3, v0
	ds_write_b32 v147, v0
